# sc1 write-through on G1/G2/G3 epilogue and norm Y stores
# speedup vs baseline: 1.0086x; 1.0086x over previous
; __device__ __forceinline__ unsigned cvt_pk_bf16(float lo, float hi) { unsigned r; asm volatile("v_cvt_pk_bf16_f32 %0, %1, %2" : "=v"(r) : "v"(lo), "v"(hi)); return r; }
; __device__ __forceinline__ void norm_phase(const Args& a, LAS unsigned char* lds, int l, int j, int l2, int j2, int nrows, float wgt, int tid, int G) {
;     ...
;         if (final_out) {
;             float* orow = a.out + (size_t)row * DM;
; #pragma unroll
;             for (int k = 0; k < 4; ++k) *(f32x4*)(orow + 512 * (k >> 1) + cl + 4 * (k & 1)) = sv[k];
;         } else {
;             __builtin_nontemporal_store((u32x4){cvt_pk_bf16(sv[0][0], sv[0][1]), cvt_pk_bf16(sv[0][2], sv[0][3]), cvt_pk_bf16(sv[1][0], sv[1][1]), cvt_pk_bf16(sv[1][2], sv[1][3])}, (u32x4*)(S16 + (size_t)row * DM + cl));
;             __builtin_nontemporal_store((u32x4){cvt_pk_bf16(sv[2][0], sv[2][1]), cvt_pk_bf16(sv[2][2], sv[2][3]), cvt_pk_bf16(sv[3][0], sv[3][1]), cvt_pk_bf16(sv[3][2], sv[3][3])}, (u32x4*)(S16 + (size_t)row * DM + 512 + cl));
;         }
;         if (l2 < DEPTH) {
;             float ss = 0.f;
; #pragma unroll
;             for (int k = 0; k < 4; ++k) ss += (sv[k][0] * sv[k][0] + sv[k][1] * sv[k][1]) + (sv[k][2] * sv[k][2] + sv[k][3] * sv[k][3]);
;             ss = wave_sum(ss);
;             const float rstd = rsqrtf(ss * (1.0f / DM) + EPSV);
;             f32x4 y[4];
; #pragma unroll
;             for (int k = 0; k < 4; ++k) y[k] = (sv[k] * rstd) * Bv[k] + Cv[k];
;             *(u32x4*)(Y + (size_t)row * DM + cl) = (u32x4){cvt_pk_bf16(y[0][0], y[0][1]), cvt_pk_bf16(y[0][2], y[0][3]), cvt_pk_bf16(y[1][0], y[1][1]), cvt_pk_bf16(y[1][2], y[1][3])};
;             *(u32x4*)(Y + (size_t)row * DM + 512 + cl) = (u32x4){cvt_pk_bf16(y[2][0], y[2][1]), cvt_pk_bf16(y[2][2], y[2][3]), cvt_pk_bf16(y[3][0], y[3][1]), cvt_pk_bf16(y[3][2], y[3][3])};
;         }
;         zc0 = zn0; zc1 = zn1; qc0 = qn0; qc1 = qn1;
; #pragma unroll
;         for (int k = 0; k < 4; ++k) xc[k] = xn[k];
.LBB0_17:
	s_or_b64 exec, exec, s[18:19]
	v_mul_f32_e32 v0, v49, v49
	v_mul_f32_e32 v73, v51, v51
	v_fmac_f32_e32 v0, v48, v48
	v_fmac_f32_e32 v73, v50, v50
	v_add_f32_e32 v0, v0, v73
	v_mul_f32_e32 v73, v21, v21
	v_mul_f32_e32 v83, v23, v23
	v_fmac_f32_e32 v73, v20, v20
	v_fmac_f32_e32 v83, v22, v22
	v_add_f32_e32 v73, v73, v83
	v_add_f32_e32 v0, v73, v0
	v_mul_f32_e32 v73, v9, v9
	v_mul_f32_e32 v83, v11, v11
	v_fmac_f32_e32 v73, v8, v8
	v_fmac_f32_e32 v83, v10, v10
	v_add_f32_e32 v73, v73, v83
	v_add_f32_e32 v0, v73, v0
	v_mul_f32_e32 v73, v5, v5
	v_mul_f32_e32 v83, v7, v7
	v_fmac_f32_e32 v73, v4, v4
	v_fmac_f32_e32 v83, v6, v6
	v_add_f32_e32 v73, v73, v83
	v_add_f32_e32 v0, v73, v0
	s_and_b64 s[0:1], exec, vcc
	v_ashrrev_i32_e32 v3, 31, v2
	v_add_f32_dpp v0, v0, v0 quad_perm:[1,0,3,2] row_mask:0xf bank_mask:0xf bound_ctrl:1
	v_lshlrev_b64 v[88:89], 11, v[2:3]
	v_cvt_pk_bf16_f32 v84, v48, v49
	v_cvt_pk_bf16_f32 v85, v50, v51
	v_cvt_pk_bf16_f32 v86, v20, v21
	v_cvt_pk_bf16_f32 v87, v22, v23
	s_nop 0
	v_add_f32_dpp v0, v0, v0 quad_perm:[2,3,0,1] row_mask:0xf bank_mask:0xf bound_ctrl:1
	v_lshl_add_u64 v[2:3], v[74:75], 0, v[88:89]
	global_store_dwordx4 v[2:3], v[84:87], off nt
	v_add_f32_dpp v0, v0, v0 row_half_mirror row_mask:0xf bank_mask:0xf bound_ctrl:1
	s_or_b64 s[12:13], s[0:1], s[12:13]
	v_cvt_pk_bf16_f32 v84, v8, v9
	v_cvt_pk_bf16_f32 v85, v10, v11
	v_cvt_pk_bf16_f32 v86, v4, v5
	v_cvt_pk_bf16_f32 v87, v6, v7
	s_nop 0
	v_add_f32_dpp v0, v0, v0 row_mirror row_mask:0xf bank_mask:0xf bound_ctrl:1
	v_mov_b32_e32 v73, v0
	s_nop 1
	v_permlane16_swap_b32_e32 v0, v73
	v_add_f32_e32 v0, v0, v73
	v_mov_b32_e32 v73, v0
	s_nop 1
	v_permlane32_swap_b32_e32 v0, v73
	v_add_f32_e32 v0, v0, v73
	v_fmamk_f32 v0, v0, 0x3a800000, v185
	v_mul_f32_e32 v73, 0x4b800000, v0
	v_cmp_gt_f32_e32 vcc, s16, v0
	global_store_dwordx4 v[2:3], v[84:87], off offset:1024 nt
	s_add_i32 s3, s3, 1
	v_cndmask_b32_e32 v0, v0, v73, vcc
	v_rsq_f32_e32 v0, v0
	v_mov_b32_e32 v73, v82
	v_mul_f32_e32 v2, 0x45800000, v0
	v_cndmask_b32_e32 v0, v0, v2, vcc
	v_pk_mul_f32 v[2:3], v[48:49], v[0:1] op_sel_hi:[1,0]
	v_pk_mul_f32 v[20:21], v[20:21], v[0:1] op_sel_hi:[1,0]
	v_pk_mul_f32 v[48:49], v[50:51], v[0:1] op_sel_hi:[1,0]
	s_waitcnt lgkmcnt(5)
	v_pk_fma_f32 v[2:3], v[16:17], v[2:3], v[40:41]
	v_pk_mul_f32 v[22:23], v[22:23], v[0:1] op_sel_hi:[1,0]
	s_waitcnt lgkmcnt(4)
	v_pk_fma_f32 v[20:21], v[28:29], v[20:21], v[32:33]
	v_pk_mul_f32 v[4:5], v[4:5], v[0:1] op_sel_hi:[1,0]
	v_pk_fma_f32 v[48:49], v[18:19], v[48:49], v[42:43]
	v_pk_fma_f32 v[22:23], v[30:31], v[22:23], v[34:35]
	v_pk_mul_f32 v[8:9], v[8:9], v[0:1] op_sel_hi:[1,0]
	v_pk_mul_f32 v[10:11], v[10:11], v[0:1] op_sel_hi:[1,0]
	v_pk_mul_f32 v[6:7], v[6:7], v[0:1] op_sel_hi:[1,0]
	s_waitcnt vmcnt(3) lgkmcnt(0)
	v_pk_fma_f32 v[50:51], v[64:65], v[4:5], v[56:57]
	v_cvt_pk_bf16_f32 v2, v2, v3
	v_cvt_pk_bf16_f32 v3, v48, v49
	v_cvt_pk_bf16_f32 v4, v20, v21
	v_cvt_pk_bf16_f32 v5, v22, v23
	v_lshl_add_u64 v[20:21], v[76:77], 0, v[88:89]
	s_waitcnt vmcnt(2)
	v_pk_fma_f32 v[10:11], v[54:55], v[10:11], v[62:63]
	v_pk_fma_f32 v[8:9], v[52:53], v[8:9], v[60:61]
	v_pk_fma_f32 v[6:7], v[66:67], v[6:7], v[58:59]
	global_store_dwordx4 v[20:21], v[2:5], off sc1
	s_nop 1
	v_cvt_pk_bf16_f32 v2, v8, v9
	v_cvt_pk_bf16_f32 v3, v10, v11
	v_cvt_pk_bf16_f32 v4, v50, v51
	v_cvt_pk_bf16_f32 v5, v6, v7
	global_store_dwordx4 v[20:21], v[2:5], off offset:1024 sc1
	v_mov_b64_e32 v[8:9], v[44:45]
	v_mov_b64_e32 v[22:23], v[14:15]
	v_mov_b64_e32 v[4:5], v[36:37]
	v_mov_b64_e32 v[50:51], v[26:27]
	v_mov_b64_e32 v[6:7], v[38:39]
	v_mov_b64_e32 v[10:11], v[46:47]
	v_mov_b64_e32 v[20:21], v[12:13]
	v_mov_b64_e32 v[48:49], v[24:25]
	s_andn2_b64 exec, exec, s[12:13]
	s_cbranch_execz .LBB0_87

; #define PG8_STAGE(bufoff, gbase, voff) do { _Pragma("unroll") for (int _i = 0; _i < 2; ++_i) \
;         __builtin_amdgcn_global_load_lds((const unsigned*)((const char*)(gbase) + (voff)[_i]), (LAS unsigned*)(lds + (bufoff) + ldsw + _i * 8192), 16, 0, 0); } while (0)
; #define PG8_LDA(dst, b, h) do { _Pragma("unroll") for (int m = 0; m < 4; ++m) _Pragma("unroll") for (int k = 0; k < 2; ++k) dst[m][k] = *(const LAS bf16x8*)(lds + PG8_SA(b, h) + aoff + m * 2048 + k * 1024); } while (0)
; #define PG8_LDB(dst, b, h) do { _Pragma("unroll") for (int n = 0; n < 2; ++n) _Pragma("unroll") for (int k = 0; k < 2; ++k) dst[n][k] = *(const LAS bf16x8*)(lds + PG8_SB(b, h) + boff + n * 2048 + k * 1024); } while (0)
; #define PG8_MMA(ai, bj, At, Bt) do { __builtin_amdgcn_s_setprio(1); _Pragma("unroll") for (int m = 0; m < 4; ++m) _Pragma("unroll") for (int n = 0; n < 2; ++n) _Pragma("unroll") for (int k = 0; k < 2; ++k) \
;         acc[ai][bj][m][n] = __builtin_amdgcn_mfma_f32_16x16x32_bf16(Bt[n][k], At[m][k], acc[ai][bj][m][n], 0, 0, 0); __builtin_amdgcn_s_setprio(0); } while (0)
; #define PG8_WAIT_V(n) asm volatile("s_waitcnt vmcnt(" #n ")" ::: "memory")
; #define PG8_WAIT_L(n) asm volatile("s_waitcnt lgkmcnt(" #n ")" ::: "memory")
; #define PG8_BAR __builtin_amdgcn_s_barrier()
; #define PG8_SCHED __builtin_amdgcn_sched_barrier(0)
; template <class Epi, class Sched, bool ALIGN_EPI = false, bool SP2 = false>
; __device__ __forceinline__ void gemm_phase(LAS unsigned char* lds, const Gemm g, const Sched& S, const Epi& E, const int tid) {
;     ...
;             PG8_LDB(B0, 0, 0); PG8_LDB(B1, 0, 1); PG8_SCHED; PG8_LDA(At, 0, 0); PG8_STAGE(PG8_SA(1, 1), a1 + hstep, voffA);
;             PG8_WAIT_V(8); PG8_WAIT_L(0); PG8_BAR; PG8_MMA(0, 0, At, B0); PG8_MMA(0, 1, At, B1); PG8_BAR; PG8_SCHED;
.LBB0_531:
	s_add_i32 s54, s28, 2
	s_add_u32 s55, s24, 0x80
	s_addc_u32 s29, s25, 0
	s_add_i32 s57, 0, 0x10000
	s_cmp_eq_u32 s21, s28
	s_cselect_b32 s29, s23, s29
	s_cselect_b32 s28, s22, s55
	v_add_u32_e32 v140, s57, v143
	s_cselect_b32 s61, s1, s53
	s_cselect_b32 s60, s0, s52
	s_add_i32 s55, 0, 0x14000
	ds_read_b128 v[146:149], v140
	ds_read_b128 v[150:153], v140 offset:1024
	ds_read_b128 v[154:157], v140 offset:2048
	ds_read_b128 v[160:163], v140 offset:3072
	v_add_u32_e32 v140, s55, v143
	ds_read_b128 v[164:167], v140
	ds_read_b128 v[168:171], v140 offset:1024
	ds_read_b128 v[172:175], v140 offset:2048
	ds_read_b128 v[176:179], v140 offset:3072
	v_lshl_add_u64 v[140:141], s[24:25], 0, v[138:139]
	s_add_i32 m0, s31, 0xc000
	ds_read_b128 v[180:183], v145
	ds_read_b128 v[208:211], v145 offset:1024
	ds_read_b128 v[212:215], v145 offset:2048
	ds_read_b128 v[216:219], v145 offset:3072
	ds_read_b128 v[220:223], v145 offset:4096
	ds_read_b128 v[224:227], v145 offset:5120
	ds_read_b128 v[228:231], v145 offset:6144
	ds_read_b128 v[232:235], v145 offset:7168
	global_load_lds_dwordx4 v[140:141], off
	v_lshl_add_u64 v[140:141], s[24:25], 0, v[136:137]
	s_add_i32 m0, s31, 0xe000
	s_nop 0
	global_load_lds_dwordx4 v[140:141], off
	s_waitcnt vmcnt(8)
	s_waitcnt lgkmcnt(0)
	s_barrier
	s_setprio 1
	s_waitcnt lgkmcnt(0)
	v_mfma_f32_16x16x32_bf16 v[126:129], v[146:149], v[180:183], v[126:129]
	v_mfma_f32_16x16x32_bf16 v[122:125], v[154:157], v[180:183], v[122:125]
	v_mfma_f32_16x16x32_bf16 v[118:121], v[146:149], v[212:215], v[118:121]
	v_mfma_f32_16x16x32_bf16 v[110:113], v[154:157], v[212:215], v[110:113]
	v_mfma_f32_16x16x32_bf16 v[102:105], v[146:149], v[220:223], v[102:105]
	v_mfma_f32_16x16x32_bf16 v[94:97], v[154:157], v[220:223], v[94:97]
	v_mfma_f32_16x16x32_bf16 v[86:89], v[146:149], v[228:231], v[86:89]
	v_mfma_f32_16x16x32_bf16 v[78:81], v[154:157], v[228:231], v[78:81]
	v_mfma_f32_16x16x32_bf16 v[126:129], v[150:153], v[208:211], v[126:129]
	v_mfma_f32_16x16x32_bf16 v[122:125], v[160:163], v[208:211], v[122:125]
	v_mfma_f32_16x16x32_bf16 v[118:121], v[150:153], v[216:219], v[118:121]
	v_mfma_f32_16x16x32_bf16 v[110:113], v[160:163], v[216:219], v[110:113]
	v_mfma_f32_16x16x32_bf16 v[102:105], v[150:153], v[224:227], v[102:105]
	v_mfma_f32_16x16x32_bf16 v[94:97], v[160:163], v[224:227], v[94:97]
	v_mfma_f32_16x16x32_bf16 v[86:89], v[150:153], v[232:235], v[86:89]
	v_mfma_f32_16x16x32_bf16 v[78:81], v[160:163], v[232:235], v[78:81]
	s_setprio 0
	s_setprio 1
	v_mfma_f32_16x16x32_bf16 v[114:117], v[164:167], v[180:183], v[114:117]
	v_mfma_f32_16x16x32_bf16 v[106:109], v[172:175], v[180:183], v[106:109]
	v_mfma_f32_16x16x32_bf16 v[98:101], v[164:167], v[212:215], v[98:101]
	v_mfma_f32_16x16x32_bf16 v[90:93], v[172:175], v[212:215], v[90:93]
	v_mfma_f32_16x16x32_bf16 v[82:85], v[164:167], v[220:223], v[82:85]
	v_mfma_f32_16x16x32_bf16 v[74:77], v[172:175], v[220:223], v[74:77]
	v_mfma_f32_16x16x32_bf16 v[70:73], v[164:167], v[228:231], v[70:73]
	v_mfma_f32_16x16x32_bf16 v[66:69], v[172:175], v[228:231], v[66:69]
	v_mfma_f32_16x16x32_bf16 v[114:117], v[168:171], v[208:211], v[114:117]
	v_mfma_f32_16x16x32_bf16 v[106:109], v[176:179], v[208:211], v[106:109]
	v_mfma_f32_16x16x32_bf16 v[98:101], v[168:171], v[216:219], v[98:101]
	v_mfma_f32_16x16x32_bf16 v[90:93], v[176:179], v[216:219], v[90:93]
	v_mfma_f32_16x16x32_bf16 v[82:85], v[168:171], v[224:227], v[82:85]
	v_mfma_f32_16x16x32_bf16 v[74:77], v[176:179], v[224:227], v[74:77]
	v_mfma_f32_16x16x32_bf16 v[70:73], v[168:171], v[232:235], v[70:73]
	v_mfma_f32_16x16x32_bf16 v[66:69], v[176:179], v[232:235], v[66:69]
	s_setprio 0
	s_barrier
	s_add_i32 s57, s57, s26
	v_lshl_add_u64 v[140:141], s[60:61], 0, v[0:1]
	s_mov_b32 m0, s57
	ds_read_b128 v[180:183], v145 offset:16384
	ds_read_b128 v[208:211], v145 offset:17408
	ds_read_b128 v[212:215], v145 offset:18432
	ds_read_b128 v[216:219], v145 offset:19456
	ds_read_b128 v[220:223], v145 offset:20480
	ds_read_b128 v[224:227], v145 offset:21504
	ds_read_b128 v[228:231], v145 offset:22528
	ds_read_b128 v[232:235], v145 offset:23552
	global_load_lds_dwordx4 v[140:141], off
	s_add_i32 m0, s57, 0x2000
	v_lshl_add_u64 v[236:237], s[60:61], 0, v[130:131]
	s_add_u32 s60, s60, s16
	s_addc_u32 s61, s61, 0
	s_add_i32 s55, s55, s26
	global_load_lds_dwordx4 v[236:237], off
	v_lshl_add_u64 v[238:239], s[60:61], 0, v[0:1]
	s_mov_b32 m0, s55
	v_lshl_add_u64 v[240:241], s[60:61], 0, v[130:131]
	global_load_lds_dwordx4 v[238:239], off
	s_add_i32 m0, s55, 0x2000
	v_lshl_add_u64 v[242:243], s[28:29], 0, v[134:135]
	global_load_lds_dwordx4 v[240:241], off
	s_mov_b32 m0, s31
	v_lshl_add_u64 v[244:245], s[28:29], 0, v[132:133]
	global_load_lds_dwordx4 v[242:243], off
	s_mov_b32 m0, s33
	s_nop 0
	global_load_lds_dwordx4 v[244:245], off
	s_waitcnt vmcnt(8)
	s_waitcnt lgkmcnt(0)
	s_barrier
; #define PG8_STAGE(bufoff, gbase, voff) do { _Pragma("unroll") for (int _i = 0; _i < 2; ++_i) \
;         __builtin_amdgcn_global_load_lds((const unsigned*)((const char*)(gbase) + (voff)[_i]), (LAS unsigned*)(lds + (bufoff) + ldsw + _i * 8192), 16, 0, 0); } while (0)
; #define PG8_LDA(dst, b, h) do { _Pragma("unroll") for (int m = 0; m < 4; ++m) _Pragma("unroll") for (int k = 0; k < 2; ++k) dst[m][k] = *(const LAS bf16x8*)(lds + PG8_SA(b, h) + aoff + m * 2048 + k * 1024); } while (0)
; #define PG8_LDB(dst, b, h) do { _Pragma("unroll") for (int n = 0; n < 2; ++n) _Pragma("unroll") for (int k = 0; k < 2; ++k) dst[n][k] = *(const LAS bf16x8*)(lds + PG8_SB(b, h) + boff + n * 2048 + k * 1024); } while (0)
; #define PG8_MMA(ai, bj, At, Bt) do { __builtin_amdgcn_s_setprio(1); _Pragma("unroll") for (int m = 0; m < 4; ++m) _Pragma("unroll") for (int n = 0; n < 2; ++n) _Pragma("unroll") for (int k = 0; k < 2; ++k) \
;         acc[ai][bj][m][n] = __builtin_amdgcn_mfma_f32_16x16x32_bf16(Bt[n][k], At[m][k], acc[ai][bj][m][n], 0, 0, 0); __builtin_amdgcn_s_setprio(0); } while (0)
; #define PG8_WAIT_V(n) asm volatile("s_waitcnt vmcnt(" #n ")" ::: "memory")
; #define PG8_WAIT_L(n) asm volatile("s_waitcnt lgkmcnt(" #n ")" ::: "memory")
; #define PG8_BAR __builtin_amdgcn_s_barrier()
; #define PG8_SCHED __builtin_amdgcn_sched_barrier(0)
; template <class Epi, class Sched, bool ALIGN_EPI = false, bool SP2 = false>
; __device__ __forceinline__ void gemm_phase(LAS unsigned char* lds, const Gemm g, const Sched& S, const Epi& E, const int tid) {
;     ...
;             PG8_WAIT_V(8); PG8_WAIT_L(0); PG8_BAR; PG8_MMA(1, 0, At, B0); PG8_MMA(1, 1, At, B1); PG8_BAR; PG8_SCHED;
;             PG8_LDB(B0, 1, 0); PG8_LDB(B1, 1, 1); PG8_SCHED; PG8_LDA(At, 1, 0); PG8_STAGE(PG8_SA(0, 1), a2 + hstep, voffA);
;             PG8_WAIT_V(8); PG8_WAIT_L(0); PG8_BAR; PG8_MMA(0, 0, At, B0); PG8_MMA(0, 1, At, B1); PG8_BAR; PG8_SCHED;
	s_setprio 1
	s_waitcnt lgkmcnt(0)
	v_mfma_f32_16x16x32_bf16 v[62:65], v[146:149], v[180:183], v[62:65]
	v_mfma_f32_16x16x32_bf16 v[58:61], v[154:157], v[180:183], v[58:61]
	v_mfma_f32_16x16x32_bf16 v[54:57], v[146:149], v[212:215], v[54:57]
	v_mfma_f32_16x16x32_bf16 v[46:49], v[154:157], v[212:215], v[46:49]
	v_mfma_f32_16x16x32_bf16 v[38:41], v[146:149], v[220:223], v[38:41]
	v_mfma_f32_16x16x32_bf16 v[30:33], v[154:157], v[220:223], v[30:33]
	v_mfma_f32_16x16x32_bf16 v[22:25], v[146:149], v[228:231], v[22:25]
	v_mfma_f32_16x16x32_bf16 v[14:17], v[154:157], v[228:231], v[14:17]
	v_mfma_f32_16x16x32_bf16 v[62:65], v[150:153], v[208:211], v[62:65]
	v_mfma_f32_16x16x32_bf16 v[58:61], v[160:163], v[208:211], v[58:61]
	v_mfma_f32_16x16x32_bf16 v[54:57], v[150:153], v[216:219], v[54:57]
	v_mfma_f32_16x16x32_bf16 v[46:49], v[160:163], v[216:219], v[46:49]
	v_mfma_f32_16x16x32_bf16 v[38:41], v[150:153], v[224:227], v[38:41]
	v_mfma_f32_16x16x32_bf16 v[30:33], v[160:163], v[224:227], v[30:33]
	v_mfma_f32_16x16x32_bf16 v[22:25], v[150:153], v[232:235], v[22:25]
	v_mfma_f32_16x16x32_bf16 v[14:17], v[160:163], v[232:235], v[14:17]
	s_setprio 0
	s_setprio 1
	v_mfma_f32_16x16x32_bf16 v[50:53], v[164:167], v[180:183], v[50:53]
	v_mfma_f32_16x16x32_bf16 v[42:45], v[172:175], v[180:183], v[42:45]
	v_mfma_f32_16x16x32_bf16 v[34:37], v[164:167], v[212:215], v[34:37]
	v_mfma_f32_16x16x32_bf16 v[26:29], v[172:175], v[212:215], v[26:29]
	v_mfma_f32_16x16x32_bf16 v[18:21], v[164:167], v[220:223], v[18:21]
	v_mfma_f32_16x16x32_bf16 v[10:13], v[172:175], v[220:223], v[10:13]
	v_mfma_f32_16x16x32_bf16 v[6:9], v[164:167], v[228:231], v[6:9]
	v_mfma_f32_16x16x32_bf16 v[2:5], v[172:175], v[228:231], v[2:5]
	v_mfma_f32_16x16x32_bf16 v[50:53], v[168:171], v[208:211], v[50:53]
	v_mfma_f32_16x16x32_bf16 v[42:45], v[176:179], v[208:211], v[42:45]
	v_mfma_f32_16x16x32_bf16 v[34:37], v[168:171], v[216:219], v[34:37]
	v_mfma_f32_16x16x32_bf16 v[26:29], v[176:179], v[216:219], v[26:29]
	v_mfma_f32_16x16x32_bf16 v[18:21], v[168:171], v[224:227], v[18:21]
	v_mfma_f32_16x16x32_bf16 v[10:13], v[176:179], v[224:227], v[10:13]
	v_mfma_f32_16x16x32_bf16 v[6:9], v[168:171], v[232:235], v[6:9]
	v_mfma_f32_16x16x32_bf16 v[2:5], v[176:179], v[232:235], v[2:5]
	s_setprio 0
	s_barrier
	s_add_i32 s55, 0, 0x18000
	v_add_u32_e32 v159, s55, v143
	s_add_i32 s57, 0, 0x1c000
	ds_read_b128 v[146:149], v159
	ds_read_b128 v[150:153], v159 offset:1024
	ds_read_b128 v[154:157], v159 offset:2048
	ds_read_b128 v[160:163], v159 offset:3072
	v_add_u32_e32 v159, s57, v143
	ds_read_b128 v[164:167], v159
	ds_read_b128 v[168:171], v159 offset:1024
	ds_read_b128 v[172:175], v159 offset:2048
	ds_read_b128 v[176:179], v159 offset:3072
	s_add_u32 s28, s28, s16
	s_addc_u32 s29, s29, 0
	s_mov_b32 m0, s34
	v_lshl_add_u64 v[246:247], s[28:29], 0, v[134:135]
	ds_read_b128 v[180:183], v145 offset:32768
	ds_read_b128 v[208:211], v145 offset:33792
	ds_read_b128 v[212:215], v145 offset:34816
	ds_read_b128 v[216:219], v145 offset:35840
	ds_read_b128 v[220:223], v145 offset:36864
	ds_read_b128 v[224:227], v145 offset:37888
	ds_read_b128 v[228:231], v145 offset:38912
	ds_read_b128 v[232:235], v145 offset:39936
	global_load_lds_dwordx4 v[246:247], off
	v_lshl_add_u64 v[246:247], s[28:29], 0, v[132:133]
	s_mov_b32 m0, s35
	s_nop 0
	global_load_lds_dwordx4 v[246:247], off
	s_waitcnt vmcnt(8)
	s_waitcnt lgkmcnt(0)
	s_barrier
	s_setprio 1
	s_waitcnt lgkmcnt(0)
	v_mfma_f32_16x16x32_bf16 v[126:129], v[146:149], v[180:183], v[126:129]
	v_mfma_f32_16x16x32_bf16 v[122:125], v[154:157], v[180:183], v[122:125]
	v_mfma_f32_16x16x32_bf16 v[118:121], v[146:149], v[212:215], v[118:121]
	v_mfma_f32_16x16x32_bf16 v[110:113], v[154:157], v[212:215], v[110:113]
	v_mfma_f32_16x16x32_bf16 v[102:105], v[146:149], v[220:223], v[102:105]
	v_mfma_f32_16x16x32_bf16 v[94:97], v[154:157], v[220:223], v[94:97]
	v_mfma_f32_16x16x32_bf16 v[86:89], v[146:149], v[228:231], v[86:89]
	v_mfma_f32_16x16x32_bf16 v[78:81], v[154:157], v[228:231], v[78:81]
	v_mfma_f32_16x16x32_bf16 v[126:129], v[150:153], v[208:211], v[126:129]
	v_mfma_f32_16x16x32_bf16 v[122:125], v[160:163], v[208:211], v[122:125]
	v_mfma_f32_16x16x32_bf16 v[118:121], v[150:153], v[216:219], v[118:121]
	v_mfma_f32_16x16x32_bf16 v[110:113], v[160:163], v[216:219], v[110:113]
	v_mfma_f32_16x16x32_bf16 v[102:105], v[150:153], v[224:227], v[102:105]
	v_mfma_f32_16x16x32_bf16 v[94:97], v[160:163], v[224:227], v[94:97]
	v_mfma_f32_16x16x32_bf16 v[86:89], v[150:153], v[232:235], v[86:89]
	v_mfma_f32_16x16x32_bf16 v[78:81], v[160:163], v[232:235], v[78:81]
	s_setprio 0
	s_setprio 1
	v_mfma_f32_16x16x32_bf16 v[114:117], v[164:167], v[180:183], v[114:117]
	v_mfma_f32_16x16x32_bf16 v[106:109], v[172:175], v[180:183], v[106:109]
	v_mfma_f32_16x16x32_bf16 v[98:101], v[164:167], v[212:215], v[98:101]
	v_mfma_f32_16x16x32_bf16 v[90:93], v[172:175], v[212:215], v[90:93]
	v_mfma_f32_16x16x32_bf16 v[82:85], v[164:167], v[220:223], v[82:85]
	v_mfma_f32_16x16x32_bf16 v[74:77], v[172:175], v[220:223], v[74:77]
	v_mfma_f32_16x16x32_bf16 v[70:73], v[164:167], v[228:231], v[70:73]
	v_mfma_f32_16x16x32_bf16 v[66:69], v[172:175], v[228:231], v[66:69]
	v_mfma_f32_16x16x32_bf16 v[114:117], v[168:171], v[208:211], v[114:117]
	v_mfma_f32_16x16x32_bf16 v[106:109], v[176:179], v[208:211], v[106:109]
	v_mfma_f32_16x16x32_bf16 v[98:101], v[168:171], v[216:219], v[98:101]
	v_mfma_f32_16x16x32_bf16 v[90:93], v[176:179], v[216:219], v[90:93]
	v_mfma_f32_16x16x32_bf16 v[82:85], v[168:171], v[224:227], v[82:85]
	v_mfma_f32_16x16x32_bf16 v[74:77], v[176:179], v[224:227], v[74:77]
	v_mfma_f32_16x16x32_bf16 v[70:73], v[168:171], v[232:235], v[70:73]
	v_mfma_f32_16x16x32_bf16 v[66:69], v[176:179], v[232:235], v[66:69]
	s_setprio 0
	s_barrier
; #define PG8_STAGE(bufoff, gbase, voff) do { _Pragma("unroll") for (int _i = 0; _i < 2; ++_i) \
;         __builtin_amdgcn_global_load_lds((const unsigned*)((const char*)(gbase) + (voff)[_i]), (LAS unsigned*)(lds + (bufoff) + ldsw + _i * 8192), 16, 0, 0); } while (0)
; #define PG8_LDA(dst, b, h) do { _Pragma("unroll") for (int m = 0; m < 4; ++m) _Pragma("unroll") for (int k = 0; k < 2; ++k) dst[m][k] = *(const LAS bf16x8*)(lds + PG8_SA(b, h) + aoff + m * 2048 + k * 1024); } while (0)
; #define PG8_MMA(ai, bj, At, Bt) do { __builtin_amdgcn_s_setprio(1); _Pragma("unroll") for (int m = 0; m < 4; ++m) _Pragma("unroll") for (int n = 0; n < 2; ++n) _Pragma("unroll") for (int k = 0; k < 2; ++k) \
;         acc[ai][bj][m][n] = __builtin_amdgcn_mfma_f32_16x16x32_bf16(Bt[n][k], At[m][k], acc[ai][bj][m][n], 0, 0, 0); __builtin_amdgcn_s_setprio(0); } while (0)
; #define PG8_WAIT_V(n) asm volatile("s_waitcnt vmcnt(" #n ")" ::: "memory")
; #define PG8_WAIT_L(n) asm volatile("s_waitcnt lgkmcnt(" #n ")" ::: "memory")
; #define PG8_BAR __builtin_amdgcn_s_barrier()
; #define PG8_SCHED __builtin_amdgcn_sched_barrier(0)
; template <class Epi, class Sched, bool ALIGN_EPI = false, bool SP2 = false>
; __device__ __forceinline__ void gemm_phase(LAS unsigned char* lds, const Gemm g, const Sched& S, const Epi& E, const int tid) {
;     ...
;             PG8_LDA(At, 1, 1); PG8_STAGE(PG8_SB(1, 0), b3, voffB); PG8_STAGE(PG8_SB(1, 1), b3 + hstep, voffB); PG8_STAGE(PG8_SA(1, 0), a3, voffA);
;             PG8_WAIT_V(8); PG8_WAIT_L(0); PG8_BAR; PG8_MMA(1, 0, At, B0); PG8_MMA(1, 1, At, B1); PG8_BAR; PG8_SCHED;
	s_add_i32 s28, s55, s26
	v_lshl_add_u64 v[140:141], v[140:141], 0, s[36:37]
	s_mov_b32 m0, s28
	ds_read_b128 v[180:183], v145 offset:49152
	ds_read_b128 v[208:211], v145 offset:50176
	ds_read_b128 v[212:215], v145 offset:51200
	ds_read_b128 v[216:219], v145 offset:52224
	ds_read_b128 v[220:223], v145 offset:53248
	ds_read_b128 v[224:227], v145 offset:54272
	ds_read_b128 v[228:231], v145 offset:55296
	ds_read_b128 v[232:235], v145 offset:56320
	global_load_lds_dwordx4 v[140:141], off
	v_lshl_add_u64 v[140:141], v[236:237], 0, s[36:37]
	s_add_i32 m0, s28, 0x2000
	s_add_i32 s28, s57, s26
	global_load_lds_dwordx4 v[140:141], off
	v_lshl_add_u64 v[140:141], v[238:239], 0, s[36:37]
	s_mov_b32 m0, s28
	s_nop 0
	global_load_lds_dwordx4 v[140:141], off
	v_lshl_add_u64 v[140:141], v[240:241], 0, s[36:37]
	s_add_i32 m0, s28, 0x2000
	s_nop 0
	global_load_lds_dwordx4 v[140:141], off
	v_lshl_add_u64 v[140:141], v[242:243], 0, s[36:37]
	s_mov_b32 m0, s41
	s_nop 0
	global_load_lds_dwordx4 v[140:141], off
	v_lshl_add_u64 v[140:141], v[244:245], 0, s[36:37]
	s_mov_b32 m0, s42
	s_nop 0
	global_load_lds_dwordx4 v[140:141], off
	s_waitcnt vmcnt(8)
	s_waitcnt lgkmcnt(0)
	s_barrier
	s_setprio 1
	s_waitcnt lgkmcnt(0)
	v_mfma_f32_16x16x32_bf16 v[62:65], v[146:149], v[180:183], v[62:65]
	v_mfma_f32_16x16x32_bf16 v[58:61], v[154:157], v[180:183], v[58:61]
	v_mfma_f32_16x16x32_bf16 v[54:57], v[146:149], v[212:215], v[54:57]
	v_mfma_f32_16x16x32_bf16 v[46:49], v[154:157], v[212:215], v[46:49]
	v_mfma_f32_16x16x32_bf16 v[38:41], v[146:149], v[220:223], v[38:41]
	v_mfma_f32_16x16x32_bf16 v[30:33], v[154:157], v[220:223], v[30:33]
	v_mfma_f32_16x16x32_bf16 v[22:25], v[146:149], v[228:231], v[22:25]
	v_mfma_f32_16x16x32_bf16 v[14:17], v[154:157], v[228:231], v[14:17]
	v_mfma_f32_16x16x32_bf16 v[62:65], v[150:153], v[208:211], v[62:65]
	v_mfma_f32_16x16x32_bf16 v[58:61], v[160:163], v[208:211], v[58:61]
	v_mfma_f32_16x16x32_bf16 v[54:57], v[150:153], v[216:219], v[54:57]
	v_mfma_f32_16x16x32_bf16 v[46:49], v[160:163], v[216:219], v[46:49]
	v_mfma_f32_16x16x32_bf16 v[38:41], v[150:153], v[224:227], v[38:41]
	v_mfma_f32_16x16x32_bf16 v[30:33], v[160:163], v[224:227], v[30:33]
	v_mfma_f32_16x16x32_bf16 v[22:25], v[150:153], v[232:235], v[22:25]
	v_mfma_f32_16x16x32_bf16 v[14:17], v[160:163], v[232:235], v[14:17]
	s_setprio 0
	s_setprio 1
	v_mfma_f32_16x16x32_bf16 v[50:53], v[164:167], v[180:183], v[50:53]
	v_mfma_f32_16x16x32_bf16 v[42:45], v[172:175], v[180:183], v[42:45]
	v_mfma_f32_16x16x32_bf16 v[34:37], v[164:167], v[212:215], v[34:37]
	v_mfma_f32_16x16x32_bf16 v[26:29], v[172:175], v[212:215], v[26:29]
	v_mfma_f32_16x16x32_bf16 v[18:21], v[164:167], v[220:223], v[18:21]
	v_mfma_f32_16x16x32_bf16 v[10:13], v[172:175], v[220:223], v[10:13]
	v_mfma_f32_16x16x32_bf16 v[6:9], v[164:167], v[228:231], v[6:9]
	v_mfma_f32_16x16x32_bf16 v[2:5], v[172:175], v[228:231], v[2:5]
	v_mfma_f32_16x16x32_bf16 v[50:53], v[168:171], v[208:211], v[50:53]
	v_mfma_f32_16x16x32_bf16 v[42:45], v[176:179], v[208:211], v[42:45]
	v_mfma_f32_16x16x32_bf16 v[34:37], v[168:171], v[216:219], v[34:37]
	v_mfma_f32_16x16x32_bf16 v[26:29], v[176:179], v[216:219], v[26:29]
	v_mfma_f32_16x16x32_bf16 v[18:21], v[168:171], v[224:227], v[18:21]
	v_mfma_f32_16x16x32_bf16 v[10:13], v[176:179], v[224:227], v[10:13]
	v_mfma_f32_16x16x32_bf16 v[6:9], v[168:171], v[232:235], v[6:9]
	v_mfma_f32_16x16x32_bf16 v[2:5], v[176:179], v[232:235], v[2:5]
	s_setprio 0
	s_barrier
	s_add_u32 s52, s52, 0x100
	s_addc_u32 s53, s53, 0
	s_add_u32 s24, s24, 0x100
	s_addc_u32 s25, s25, 0
	s_cmp_ge_i32 s54, s48
	s_mov_b32 s28, s54
	s_cbranch_scc0 .LBB0_531
; __device__ __forceinline__ unsigned cvt_pk_bf16(float lo, float hi) { unsigned r; asm volatile("v_cvt_pk_bf16_f32 %0, %1, %2" : "=v"(r) : "v"(lo), "v"(hi)); return r; }
; #define PG8_WAIT_V(n) asm volatile("s_waitcnt vmcnt(" #n ")" ::: "memory")
; #define PG8_BAR __builtin_amdgcn_s_barrier()
;     __device__ __forceinline__ void operator()(const f32x4 (&acc)[2][2][4][2], const Unit& u, int wr, int wc, int fr, int fq) const {
;         const int row0 = u.pm * BM + wr * 64 + fr + (u.part > 0 ? u.part * T_CTX : 0), col0 = u.pn * BM + wc * 32 + 8 * fq;
; #pragma unroll
;         for (int ai = 0; ai < 2; ++ai)
; #pragma unroll
;             for (int m = 0; m < 4; ++m) {
;                 bf16_t* p = Z + (size_t)(row0 + ai * HALF + m * 16) * DM + col0;
; #pragma unroll
;                 for (int bj = 0; bj < 2; ++bj) { const f32x4 v0 = acc[ai][bj][m][0], v1 = acc[ai][bj][m][1];
;                     *(u32x4*)(p + bj * HALF) = (u32x4){cvt_pk_bf16(v0[0], v0[1]), cvt_pk_bf16(v0[2], v0[3]), cvt_pk_bf16(v1[0], v1[1]), cvt_pk_bf16(v1[2], v1[3])}; }
;             }
;     }
; template <class Epi, class Sched, bool ALIGN_EPI = false, bool SP2 = false>
; __device__ __forceinline__ void gemm_phase(LAS unsigned char* lds, const Gemm g, const Sched& S, const Epi& E, const int tid) {
;     ...
;         if (!has_next) break;
; #pragma unroll
;         for (int a = 0; a < 2; ++a)
; #pragma unroll
;             for (int b = 0; b < 2; ++b)
; #pragma unroll
;                 for (int m = 0; m < 4; ++m)
; #pragma unroll
;                     for (int n = 0; n < 2; ++n) acc[a][b][m][n] = (f32x4){0.f, 0.f, 0.f, 0.f};
;         cur = nxt; cA = nA; cB = nB; ++ui;
;         if constexpr (ALIGN_EPI) { if (wr == 1) PG8_BAR; }
;     }
;     PG8_WAIT_V(0);
;     if constexpr (!ALIGN_EPI) { if (wr == 0) PG8_BAR; }
;     PG8_BAR;
	s_max_i32 s24, s49, 0
	s_lshl_b32 s21, s51, 8
	s_lshl_b32 s24, s24, 11
	s_add_i32 s21, s21, s24
	v_add_u32_e32 v146, s21, v142
	v_lshl_or_b32 v140, s50, 8, v144
	v_ashrrev_i32_e32 v147, 31, v146
	v_ashrrev_i32_e32 v141, 31, v140
	v_lshlrev_b64 v[148:149], 11, v[146:147]
	v_lshl_add_u64 v[148:149], s[12:13], 0, v[148:149]
	v_lshlrev_b64 v[150:151], 1, v[140:141]
	v_lshl_add_u64 v[140:141], v[148:149], 0, v[150:151]
	v_cvt_pk_bf16_f32 v126, v126, v127
	v_cvt_pk_bf16_f32 v127, v128, v129
	v_cvt_pk_bf16_f32 v128, v122, v123
	v_cvt_pk_bf16_f32 v129, v124, v125
	flat_store_dwordx4 v[140:141], v[126:129] sc1
	v_cvt_pk_bf16_f32 v114, v114, v115
	v_cvt_pk_bf16_f32 v115, v116, v117
	v_cvt_pk_bf16_f32 v116, v106, v107
	v_or_b32_e32 v106, 16, v146
	v_ashrrev_i32_e32 v107, 31, v106
	v_lshlrev_b64 v[106:107], 11, v[106:107]
	v_lshl_add_u64 v[106:107], s[12:13], 0, v[106:107]
	v_cvt_pk_bf16_f32 v117, v108, v109
	flat_store_dwordx4 v[140:141], v[114:117] offset:256 sc1
	s_mov_b32 s21, 0x40000
	s_mov_b64 s[24:25], 0x40000
	v_lshl_add_u64 v[114:115], v[106:107], 0, v[150:151]
	v_cvt_pk_bf16_f32 v106, v118, v119
	v_cvt_pk_bf16_f32 v107, v120, v121
	v_cvt_pk_bf16_f32 v108, v110, v111
	v_cvt_pk_bf16_f32 v109, v112, v113
	flat_store_dwordx4 v[114:115], v[106:109] sc1
	v_cvt_pk_bf16_f32 v98, v98, v99
	v_cvt_pk_bf16_f32 v99, v100, v101
	v_cvt_pk_bf16_f32 v100, v90, v91
	v_or_b32_e32 v90, 32, v146
	v_ashrrev_i32_e32 v91, 31, v90
	v_lshlrev_b64 v[90:91], 11, v[90:91]
	v_lshl_add_u64 v[90:91], s[12:13], 0, v[90:91]
	v_cvt_pk_bf16_f32 v101, v92, v93
	flat_store_dwordx4 v[114:115], v[98:101] offset:256 sc1
	s_mov_b32 s49, s44
	s_mov_b32 s48, s46
	v_lshl_add_u64 v[98:99], v[90:91], 0, v[150:151]
	v_cvt_pk_bf16_f32 v90, v102, v103
	v_cvt_pk_bf16_f32 v91, v104, v105
	v_cvt_pk_bf16_f32 v92, v94, v95
	v_cvt_pk_bf16_f32 v93, v96, v97
	flat_store_dwordx4 v[98:99], v[90:93] sc1
	v_cvt_pk_bf16_f32 v82, v82, v83
	v_cvt_pk_bf16_f32 v83, v84, v85
	v_cvt_pk_bf16_f32 v84, v74, v75
	v_or_b32_e32 v74, 48, v146
	v_ashrrev_i32_e32 v75, 31, v74
	v_lshlrev_b64 v[74:75], 11, v[74:75]
	v_lshl_add_u64 v[74:75], s[12:13], 0, v[74:75]
	v_cvt_pk_bf16_f32 v85, v76, v77
	flat_store_dwordx4 v[98:99], v[82:85] offset:256 sc1
	s_mov_b32 s50, s47
	s_mov_b32 s51, s45
	v_lshl_add_u64 v[82:83], v[74:75], 0, v[150:151]
	v_cvt_pk_bf16_f32 v74, v86, v87
	v_cvt_pk_bf16_f32 v75, v88, v89
	v_cvt_pk_bf16_f32 v76, v78, v79
	v_cvt_pk_bf16_f32 v77, v80, v81
	flat_store_dwordx4 v[82:83], v[74:77] sc1
	v_cvt_pk_bf16_f32 v70, v70, v71
	v_cvt_pk_bf16_f32 v71, v72, v73
	v_cvt_pk_bf16_f32 v72, v66, v67
	v_cvt_pk_bf16_f32 v73, v68, v69
	flat_store_dwordx4 v[82:83], v[70:73] offset:256 sc1
	v_cvt_pk_bf16_f32 v62, v62, v63
	v_cvt_pk_bf16_f32 v63, v64, v65
	v_cvt_pk_bf16_f32 v64, v58, v59
	v_add_co_u32_e32 v58, vcc, s21, v140
	v_lshl_add_u64 v[66:67], v[140:141], 0, s[24:25]
	s_nop 0
	v_addc_co_u32_e32 v59, vcc, 0, v141, vcc
	s_mov_b32 s21, 0x48000
	v_cvt_pk_bf16_f32 v65, v60, v61
	flat_store_dwordx4 v[58:59], v[62:65] sc1
	v_cvt_pk_bf16_f32 v50, v50, v51
	v_cvt_pk_bf16_f32 v51, v52, v53
	v_cvt_pk_bf16_f32 v52, v42, v43
	v_cvt_pk_bf16_f32 v53, v44, v45
	flat_store_dwordx4 v[66:67], v[50:53] offset:256 sc1
	s_mov_b64 s[24:25], 0x48000
	v_cvt_pk_bf16_f32 v42, v54, v55
	v_cvt_pk_bf16_f32 v43, v56, v57
	v_cvt_pk_bf16_f32 v44, v46, v47
	v_add_co_u32_e32 v46, vcc, s21, v140
	v_lshl_add_u64 v[50:51], v[140:141], 0, s[24:25]
	s_nop 0
	v_addc_co_u32_e32 v47, vcc, 0, v141, vcc
	s_mov_b32 s21, 0x50000
	v_cvt_pk_bf16_f32 v45, v48, v49
	flat_store_dwordx4 v[46:47], v[42:45] sc1
	v_cvt_pk_bf16_f32 v34, v34, v35
	v_cvt_pk_bf16_f32 v35, v36, v37
	v_cvt_pk_bf16_f32 v36, v26, v27
	v_cvt_pk_bf16_f32 v37, v28, v29
	flat_store_dwordx4 v[50:51], v[34:37] offset:256 sc1
	s_mov_b64 s[24:25], 0x50000
	v_cvt_pk_bf16_f32 v26, v38, v39
	v_cvt_pk_bf16_f32 v27, v40, v41
	v_cvt_pk_bf16_f32 v28, v30, v31
	v_add_co_u32_e32 v30, vcc, s21, v140
	v_lshl_add_u64 v[34:35], v[140:141], 0, s[24:25]
	s_nop 0
	v_addc_co_u32_e32 v31, vcc, 0, v141, vcc
	s_mov_b32 s21, 0x58000
	v_cvt_pk_bf16_f32 v29, v32, v33
	flat_store_dwordx4 v[30:31], v[26:29] sc1
	v_cvt_pk_bf16_f32 v18, v18, v19
	v_cvt_pk_bf16_f32 v19, v20, v21
	v_cvt_pk_bf16_f32 v20, v10, v11
	v_cvt_pk_bf16_f32 v21, v12, v13
	flat_store_dwordx4 v[34:35], v[18:21] offset:256 sc1
	v_cvt_pk_bf16_f32 v10, v22, v23
	v_cvt_pk_bf16_f32 v11, v24, v25
	v_cvt_pk_bf16_f32 v12, v14, v15
	v_add_co_u32_e32 v14, vcc, s21, v140
	s_mov_b64 s[24:25], 0x58000
	s_nop 0
	v_addc_co_u32_e32 v15, vcc, 0, v141, vcc
	v_lshl_add_u64 v[18:19], v[140:141], 0, s[24:25]
	s_and_b64 vcc, exec, s[18:19]
	s_mov_b64 s[24:25], s[0:1]
	s_mov_b64 s[28:29], s[22:23]
	v_cvt_pk_bf16_f32 v13, v16, v17
	flat_store_dwordx4 v[14:15], v[10:13] sc1
	v_cvt_pk_bf16_f32 v6, v6, v7
	v_cvt_pk_bf16_f32 v7, v8, v9
	v_cvt_pk_bf16_f32 v8, v2, v3
	v_cvt_pk_bf16_f32 v9, v4, v5
	flat_store_dwordx4 v[18:19], v[6:9] offset:256 sc1
	s_cbranch_vccz .LBB0_517
	s_waitcnt vmcnt(0)
	v_readlane_b32 s60, v254, 41
	v_readlane_b32 s20, v254, 45
	s_cmpk_gt_u32 s14, 0xff
	v_readlane_b32 s61, v254, 42
	v_readlane_b32 s21, v254, 46
	s_cbranch_scc1 .LBB0_535
	s_barrier

; __device__ __forceinline__ unsigned cvt_pk_bf16(float lo, float hi) { unsigned r; asm volatile("v_cvt_pk_bf16_f32 %0, %1, %2" : "=v"(r) : "v"(lo), "v"(hi)); return r; }
; __device__ __forceinline__ void norm_phase(const Args& a, LAS unsigned char* lds, int l, int j, int l2, int j2, int nrows, float wgt, int tid, int G) {
;     ...
;         if (l2 < DEPTH) {
;             float ss = 0.f;
; #pragma unroll
;             for (int k = 0; k < 4; ++k) ss += (sv[k][0] * sv[k][0] + sv[k][1] * sv[k][1]) + (sv[k][2] * sv[k][2] + sv[k][3] * sv[k][3]);
;             ss = wave_sum(ss);
;             const float rstd = rsqrtf(ss * (1.0f / DM) + EPSV);
;             f32x4 y[4];
; #pragma unroll
;             for (int k = 0; k < 4; ++k) y[k] = (sv[k] * rstd) * Bv[k] + Cv[k];
;             *(u32x4*)(Y + (size_t)row * DM + cl) = (u32x4){cvt_pk_bf16(y[0][0], y[0][1]), cvt_pk_bf16(y[0][2], y[0][3]), cvt_pk_bf16(y[1][0], y[1][1]), cvt_pk_bf16(y[1][2], y[1][3])};
;             *(u32x4*)(Y + (size_t)row * DM + 512 + cl) = (u32x4){cvt_pk_bf16(y[2][0], y[2][1]), cvt_pk_bf16(y[2][2], y[2][3]), cvt_pk_bf16(y[3][0], y[3][1]), cvt_pk_bf16(y[3][2], y[3][3])};
;         }
.LBB0_580:
	v_mul_f32_e32 v58, v113, v113
	v_mul_f32_e32 v59, v115, v115
	v_fmac_f32_e32 v58, v112, v112
	v_fmac_f32_e32 v59, v114, v114
	v_add_f32_e32 v58, v58, v59
	v_mul_f32_e32 v59, v117, v117
	v_mul_f32_e32 v60, v119, v119
	v_fmac_f32_e32 v59, v116, v116
	v_fmac_f32_e32 v60, v118, v118
	v_add_f32_e32 v59, v59, v60
	v_add_f32_e32 v58, v58, v59
	v_mul_f32_e32 v59, v121, v121
	v_mul_f32_e32 v60, v123, v123
	v_fmac_f32_e32 v59, v120, v120
	v_fmac_f32_e32 v60, v122, v122
	v_add_f32_e32 v59, v59, v60
	v_add_f32_e32 v58, v59, v58
	v_mul_f32_e32 v59, v125, v125
	v_mul_f32_e32 v60, v127, v127
	v_fmac_f32_e32 v59, v124, v124
	v_fmac_f32_e32 v60, v126, v126
	v_add_f32_e32 v59, v59, v60
	v_add_f32_e32 v58, v59, v58
	s_nop 1
	v_add_f32_dpp v58, v58, v58 quad_perm:[1,0,3,2] row_mask:0xf bank_mask:0xf bound_ctrl:1
	s_nop 1
	v_add_f32_dpp v58, v58, v58 quad_perm:[2,3,0,1] row_mask:0xf bank_mask:0xf bound_ctrl:1
	s_nop 1
	v_add_f32_dpp v58, v58, v58 row_half_mirror row_mask:0xf bank_mask:0xf bound_ctrl:1
	s_nop 1
	v_add_f32_dpp v58, v58, v58 row_mirror row_mask:0xf bank_mask:0xf bound_ctrl:1
	v_mov_b32_e32 v59, v58
	s_nop 1
	v_permlane16_swap_b32_e32 v58, v59
	v_add_f32_e32 v58, v58, v59
	v_mov_b32_e32 v59, v58
	s_nop 1
	v_permlane32_swap_b32_e32 v58, v59
	v_add_f32_e32 v58, v58, v59
	v_fmamk_f32 v58, v58, 0x3a800000, v185
	v_mul_f32_e32 v59, 0x4b800000, v58
	v_cmp_gt_f32_e32 vcc, s16, v58
	s_nop 1
	v_cndmask_b32_e32 v58, v58, v59, vcc
	v_rsq_f32_e32 v58, v58
	s_nop 0
	v_mul_f32_e32 v59, 0x45800000, v58
	v_cndmask_b32_e32 v58, v58, v59, vcc
	v_pk_mul_f32 v[62:63], v[114:115], v[58:59] op_sel_hi:[1,0]
	v_pk_mul_f32 v[60:61], v[112:113], v[58:59] op_sel_hi:[1,0]
	s_waitcnt lgkmcnt(7)
	v_pk_fma_f32 v[62:63], v[4:5], v[62:63], v[16:17]
	v_pk_mul_f32 v[64:65], v[116:117], v[58:59] op_sel_hi:[1,0]
	v_pk_mul_f32 v[66:67], v[118:119], v[58:59] op_sel_hi:[1,0]
	v_pk_mul_f32 v[68:69], v[120:121], v[58:59] op_sel_hi:[1,0]
	v_pk_mul_f32 v[70:71], v[122:123], v[58:59] op_sel_hi:[1,0]
	v_pk_mul_f32 v[72:73], v[124:125], v[58:59] op_sel_hi:[1,0]
	v_pk_mul_f32 v[58:59], v[126:127], v[58:59] op_sel_hi:[1,0]
	v_pk_fma_f32 v[60:61], v[2:3], v[60:61], v[14:15]
	s_waitcnt vmcnt(1) lgkmcnt(0)
	v_pk_fma_f32 v[98:99], v[96:97], v[58:59], v[80:81]
	v_cvt_pk_bf16_f32 v58, v60, v61
	v_cvt_pk_bf16_f32 v59, v62, v63
	v_lshlrev_b64 v[62:63], 11, v[150:151]
	v_pk_fma_f32 v[66:67], v[52:53], v[66:67], v[12:13]
	v_pk_fma_f32 v[64:65], v[50:51], v[64:65], v[10:11]
	v_lshl_add_u64 v[62:63], v[146:147], 0, v[62:63]
	v_cvt_pk_bf16_f32 v60, v64, v65
	v_cvt_pk_bf16_f32 v61, v66, v67
	s_waitcnt vmcnt(0)
	v_pk_fma_f32 v[70:71], v[76:77], v[70:71], v[92:93]
	v_pk_fma_f32 v[68:69], v[74:75], v[68:69], v[90:91]
	v_pk_fma_f32 v[72:73], v[94:95], v[72:73], v[78:79]
	global_store_dwordx4 v[62:63], v[58:61], off sc1
	s_nop 1
	v_cvt_pk_bf16_f32 v58, v68, v69
	v_cvt_pk_bf16_f32 v59, v70, v71
	v_cvt_pk_bf16_f32 v60, v72, v73
	v_cvt_pk_bf16_f32 v61, v98, v99
	global_store_dwordx4 v[62:63], v[58:61], off offset:1024 sc1
	s_branch .LBB0_556

; __device__ __forceinline__ unsigned cvt_pk_bf16(float lo, float hi) { unsigned r; asm volatile("v_cvt_pk_bf16_f32 %0, %1, %2" : "=v"(r) : "v"(lo), "v"(hi)); return r; }
; #define SGLU(g_, u_) ((g_) * (u_) * __builtin_amdgcn_rcpf(1.f + __builtin_amdgcn_exp2f(-(g_))))
;     __device__ __forceinline__ void operator()(const f32x4 (&acc)[2][2][4][2], const Unit& u, int wr, int wc, int fr, int fq) const {
;         const int row0 = u.pm * BM + wr * 64 + fr, col0 = u.pn * 128 + wc * 32 + 8 * fq;
; #pragma unroll
;         for (int ai = 0; ai < 2; ++ai)
; #pragma unroll
;             for (int m = 0; m < 4; ++m) {
;                 bf16_t* p = O + (size_t)(row0 + ai * HALF + m * 16) * DFF + col0;
;                 const f32x4 g0 = acc[ai][0][m][0], g1 = acc[ai][0][m][1], u0 = acc[ai][1][m][0], u1 = acc[ai][1][m][1];
;                 u32x4 w;
;     ...
;                 w.x = cvt_pk_bf16(SGLU(g0[0], u0[0]), SGLU(g0[1], u0[1])); w.y = cvt_pk_bf16(SGLU(g0[2], u0[2]), SGLU(g0[3], u0[3]));
;                 w.z = cvt_pk_bf16(SGLU(g1[0], u1[0]), SGLU(g1[1], u1[1])); w.w = cvt_pk_bf16(SGLU(g1[2], u1[2]), SGLU(g1[3], u1[3]));
;     ...
;                 *(u32x4*)p = w;
;             }
;     }
.LBB0_595:
	v_mul_f32_e32 v122, v122, v126
	v_exp_f32_e64 v126, -v126
	v_mul_f32_e32 v123, v123, v127
	v_mul_f32_e32 v114, v114, v118
	v_exp_f32_e64 v118, -v118
	v_add_f32_e32 v126, 1.0, v126
	v_rcp_f32_e32 v126, v126
	v_mul_f32_e32 v106, v106, v110
	v_add_f32_e32 v118, 1.0, v118
	v_rcp_f32_e32 v118, v118
	v_mul_f32_e32 v122, v122, v126
	v_exp_f32_e64 v126, -v127
	v_exp_f32_e64 v110, -v110
	v_mul_f32_e32 v114, v114, v118
	v_exp_f32_e64 v118, -v119
	v_add_f32_e32 v126, 1.0, v126
	v_rcp_f32_e32 v126, v126
	v_add_f32_e32 v110, 1.0, v110
	v_add_f32_e32 v118, 1.0, v118
	v_rcp_f32_e32 v118, v118
	v_mul_f32_e32 v123, v123, v126
	v_cvt_pk_bf16_f32 v122, v122, v123
	v_mul_f32_e32 v123, v124, v128
	v_exp_f32_e64 v124, -v128
	v_rcp_f32_e32 v110, v110
	v_mul_f32_e32 v115, v115, v119
	v_mul_f32_e32 v115, v115, v118
	v_add_f32_e32 v124, 1.0, v124
	v_rcp_f32_e32 v124, v124
	v_mul_f32_e32 v106, v106, v110
	v_exp_f32_e64 v110, -v111
	v_lshl_or_b32 v142, s19, 7, v148
	v_mul_f32_e32 v123, v123, v124
	v_mul_f32_e32 v124, v125, v129
	v_exp_f32_e64 v125, -v129
	v_add_f32_e32 v110, 1.0, v110
	v_rcp_f32_e32 v110, v110
	v_lshl_add_u32 v150, s18, 8, v146
	v_add_f32_e32 v125, 1.0, v125
	v_rcp_f32_e32 v125, v125
	v_ashrrev_i32_e32 v143, 31, v142
	v_mov_b64_e32 v[140:141], s[8:9]
	v_mad_i64_i32 v[144:145], s[18:19], v150, s56, v[140:141]
	v_mul_f32_e32 v124, v124, v125
	v_cvt_pk_bf16_f32 v123, v123, v124
	v_cvt_pk_bf16_f32 v124, v114, v115
	v_exp_f32_e64 v115, -v120
	v_mul_f32_e32 v114, v116, v120
	v_exp_f32_e64 v116, -v121
	v_lshlrev_b64 v[142:143], 1, v[142:143]
	v_add_f32_e32 v115, 1.0, v115
	v_rcp_f32_e32 v115, v115
	v_add_f32_e32 v116, 1.0, v116
	v_rcp_f32_e32 v116, v116
	v_mul_f32_e32 v107, v107, v111
	v_lshl_add_u64 v[144:145], v[144:145], 0, v[142:143]
	v_mul_f32_e32 v114, v114, v115
	v_mul_f32_e32 v115, v117, v121
	v_mul_f32_e32 v107, v107, v110
	v_mul_f32_e32 v115, v115, v116
	v_cvt_pk_bf16_f32 v125, v114, v115
	flat_store_dwordx4 v[144:145], v[122:125] sc1
	v_cvt_pk_bf16_f32 v106, v106, v107
	v_mul_f32_e32 v107, v108, v112
	v_exp_f32_e64 v108, -v112
	v_mul_f32_e32 v98, v98, v102
	v_exp_f32_e64 v102, -v102
	v_mul_f32_e32 v90, v90, v94
	v_add_f32_e32 v108, 1.0, v108
	v_rcp_f32_e32 v108, v108
	v_add_f32_e32 v102, 1.0, v102
	v_rcp_f32_e32 v102, v102
	v_exp_f32_e64 v94, -v94
	v_mul_f32_e32 v107, v107, v108
	v_mul_f32_e32 v108, v109, v113
	v_exp_f32_e64 v109, -v113
	v_mul_f32_e32 v98, v98, v102
	v_exp_f32_e64 v102, -v103
	v_add_f32_e32 v94, 1.0, v94
	v_add_f32_e32 v109, 1.0, v109
	v_rcp_f32_e32 v109, v109
	v_add_f32_e32 v102, 1.0, v102
	v_rcp_f32_e32 v102, v102
	v_rcp_f32_e32 v94, v94
	v_mul_f32_e32 v99, v99, v103
	v_mul_f32_e32 v108, v108, v109
	v_mul_f32_e32 v99, v99, v102
	v_cvt_pk_bf16_f32 v107, v107, v108
	v_cvt_pk_bf16_f32 v108, v98, v99
	v_exp_f32_e64 v99, -v104
	v_mul_f32_e32 v90, v90, v94
	v_exp_f32_e64 v94, -v95
	v_mul_f32_e32 v98, v100, v104
	v_exp_f32_e64 v100, -v105
	v_add_f32_e32 v99, 1.0, v99
	v_add_f32_e32 v94, 1.0, v94
	v_rcp_f32_e32 v99, v99
	v_add_f32_e32 v100, 1.0, v100
	v_rcp_f32_e32 v94, v94
	v_rcp_f32_e32 v100, v100
	v_or_b32_e32 v114, 16, v150
	v_mad_i64_i32 v[114:115], s[18:19], v114, s56, v[140:141]
	v_mul_f32_e32 v91, v91, v95
	v_lshl_add_u64 v[114:115], v[114:115], 0, v[142:143]
	v_mul_f32_e32 v98, v98, v99
	v_mul_f32_e32 v99, v101, v105
	v_mul_f32_e32 v91, v91, v94
	v_mul_f32_e32 v99, v99, v100
	v_cvt_pk_bf16_f32 v109, v98, v99
	flat_store_dwordx4 v[114:115], v[106:109] sc1
	v_cvt_pk_bf16_f32 v90, v90, v91
	v_mul_f32_e32 v91, v92, v96
	v_exp_f32_e64 v92, -v96
	v_mul_f32_e32 v82, v82, v86
	v_exp_f32_e64 v86, -v86
	v_mul_f32_e32 v74, v74, v78
	v_add_f32_e32 v92, 1.0, v92
	v_rcp_f32_e32 v92, v92
	v_add_f32_e32 v86, 1.0, v86
	v_rcp_f32_e32 v86, v86
	v_exp_f32_e64 v78, -v78
	v_mul_f32_e32 v91, v91, v92
	v_mul_f32_e32 v92, v93, v97
	v_exp_f32_e64 v93, -v97
	v_mul_f32_e32 v82, v82, v86
	v_exp_f32_e64 v86, -v87
	v_add_f32_e32 v78, 1.0, v78
	v_add_f32_e32 v93, 1.0, v93
	v_rcp_f32_e32 v93, v93
	v_add_f32_e32 v86, 1.0, v86
	v_rcp_f32_e32 v86, v86
	v_rcp_f32_e32 v78, v78
	v_mul_f32_e32 v83, v83, v87
	v_mul_f32_e32 v92, v92, v93
	v_mul_f32_e32 v83, v83, v86
	v_cvt_pk_bf16_f32 v91, v91, v92
	v_cvt_pk_bf16_f32 v92, v82, v83
	v_exp_f32_e64 v83, -v88
	v_mul_f32_e32 v74, v74, v78
	v_exp_f32_e64 v78, -v79
	v_mul_f32_e32 v82, v84, v88
	v_exp_f32_e64 v84, -v89
	v_add_f32_e32 v83, 1.0, v83
	v_add_f32_e32 v78, 1.0, v78
	v_rcp_f32_e32 v83, v83
	v_add_f32_e32 v84, 1.0, v84
	v_rcp_f32_e32 v78, v78
	v_rcp_f32_e32 v84, v84
	v_or_b32_e32 v98, 32, v150
	v_mad_i64_i32 v[98:99], s[18:19], v98, s56, v[140:141]
	v_mul_f32_e32 v75, v75, v79
	v_lshl_add_u64 v[98:99], v[98:99], 0, v[142:143]
	v_mul_f32_e32 v82, v82, v83
	v_mul_f32_e32 v83, v85, v89
	v_mul_f32_e32 v75, v75, v78
	v_mul_f32_e32 v83, v83, v84
	v_cvt_pk_bf16_f32 v93, v82, v83
	flat_store_dwordx4 v[98:99], v[90:93] sc1
	v_cvt_pk_bf16_f32 v74, v74, v75
	v_mul_f32_e32 v75, v76, v80
	v_exp_f32_e64 v76, -v80
	v_mul_f32_e32 v66, v66, v70
	v_exp_f32_e64 v70, -v70
	v_mul_f32_e32 v58, v58, v62
	v_add_f32_e32 v76, 1.0, v76
	v_rcp_f32_e32 v76, v76
	v_add_f32_e32 v70, 1.0, v70
	v_rcp_f32_e32 v70, v70
	v_exp_f32_e64 v62, -v62
	v_mul_f32_e32 v75, v75, v76
	v_mul_f32_e32 v76, v77, v81
	v_exp_f32_e64 v77, -v81
	v_mul_f32_e32 v66, v66, v70
	v_exp_f32_e64 v70, -v71
	v_add_f32_e32 v62, 1.0, v62
	v_add_f32_e32 v77, 1.0, v77
	v_rcp_f32_e32 v77, v77
	v_add_f32_e32 v70, 1.0, v70
	v_rcp_f32_e32 v70, v70
	v_rcp_f32_e32 v62, v62
	v_mul_f32_e32 v67, v67, v71
	v_mul_f32_e32 v76, v76, v77
	v_mul_f32_e32 v67, v67, v70
	v_cvt_pk_bf16_f32 v75, v75, v76
	v_cvt_pk_bf16_f32 v76, v66, v67
	v_exp_f32_e64 v67, -v72
	v_mul_f32_e32 v58, v58, v62
; __device__ __forceinline__ unsigned cvt_pk_bf16(float lo, float hi) { unsigned r; asm volatile("v_cvt_pk_bf16_f32 %0, %1, %2" : "=v"(r) : "v"(lo), "v"(hi)); return r; }
; #define SGLU(g_, u_) ((g_) * (u_) * __builtin_amdgcn_rcpf(1.f + __builtin_amdgcn_exp2f(-(g_))))
; #define PG8_BAR __builtin_amdgcn_s_barrier()
;     __device__ __forceinline__ void operator()(const f32x4 (&acc)[2][2][4][2], const Unit& u, int wr, int wc, int fr, int fq) const {
;         const int row0 = u.pm * BM + wr * 64 + fr, col0 = u.pn * 128 + wc * 32 + 8 * fq;
; #pragma unroll
;         for (int ai = 0; ai < 2; ++ai)
; #pragma unroll
;             for (int m = 0; m < 4; ++m) {
;                 bf16_t* p = O + (size_t)(row0 + ai * HALF + m * 16) * DFF + col0;
;                 const f32x4 g0 = acc[ai][0][m][0], g1 = acc[ai][0][m][1], u0 = acc[ai][1][m][0], u1 = acc[ai][1][m][1];
;                 u32x4 w;
;     ...
;                 w.x = cvt_pk_bf16(SGLU(g0[0], u0[0]), SGLU(g0[1], u0[1])); w.y = cvt_pk_bf16(SGLU(g0[2], u0[2]), SGLU(g0[3], u0[3]));
;                 w.z = cvt_pk_bf16(SGLU(g1[0], u1[0]), SGLU(g1[1], u1[1])); w.w = cvt_pk_bf16(SGLU(g1[2], u1[2]), SGLU(g1[3], u1[3]));
;     ...
;                 *(u32x4*)p = w;
;             }
;     }
; template <class Epi, class Sched, bool ALIGN_EPI = false, bool SP2 = false>
; __device__ __forceinline__ void gemm_phase(LAS unsigned char* lds, const Gemm g, const Sched& S, const Epi& E, const int tid) {
;     ...
;         if (!has_next) break;
; #pragma unroll
;         for (int a = 0; a < 2; ++a)
; #pragma unroll
;             for (int b = 0; b < 2; ++b)
; #pragma unroll
;                 for (int m = 0; m < 4; ++m)
; #pragma unroll
;                     for (int n = 0; n < 2; ++n) acc[a][b][m][n] = (f32x4){0.f, 0.f, 0.f, 0.f};
;         cur = nxt; cA = nA; cB = nB; ++ui;
;         if constexpr (ALIGN_EPI) { if (wr == 1) PG8_BAR; }
	v_exp_f32_e64 v62, -v63
	v_mul_f32_e32 v66, v68, v72
	v_exp_f32_e64 v68, -v73
	v_add_f32_e32 v67, 1.0, v67
	v_add_f32_e32 v62, 1.0, v62
	v_rcp_f32_e32 v67, v67
	v_add_f32_e32 v68, 1.0, v68
	v_rcp_f32_e32 v62, v62
	v_rcp_f32_e32 v68, v68
	v_or_b32_e32 v82, 48, v150
	v_mad_i64_i32 v[82:83], s[18:19], v82, s56, v[140:141]
	v_mul_f32_e32 v59, v59, v63
	v_lshl_add_u64 v[82:83], v[82:83], 0, v[142:143]
	v_mul_f32_e32 v66, v66, v67
	v_mul_f32_e32 v67, v69, v73
	v_mul_f32_e32 v59, v59, v62
	v_mul_f32_e32 v67, v67, v68
	v_cvt_pk_bf16_f32 v77, v66, v67
	flat_store_dwordx4 v[82:83], v[74:77] sc1
	v_cvt_pk_bf16_f32 v58, v58, v59
	v_mul_f32_e32 v59, v60, v64
	v_exp_f32_e64 v60, -v64
	v_mul_f32_e32 v50, v50, v54
	v_exp_f32_e64 v54, -v54
	v_mul_f32_e32 v42, v42, v46
	v_add_f32_e32 v60, 1.0, v60
	v_rcp_f32_e32 v60, v60
	v_add_f32_e32 v54, 1.0, v54
	v_rcp_f32_e32 v54, v54
	v_exp_f32_e64 v46, -v46
	v_mul_f32_e32 v59, v59, v60
	v_mul_f32_e32 v60, v61, v65
	v_exp_f32_e64 v61, -v65
	v_mul_f32_e32 v50, v50, v54
	v_exp_f32_e64 v54, -v55
	v_add_f32_e32 v46, 1.0, v46
	v_add_f32_e32 v61, 1.0, v61
	v_rcp_f32_e32 v61, v61
	v_add_f32_e32 v54, 1.0, v54
	v_rcp_f32_e32 v54, v54
	v_rcp_f32_e32 v46, v46
	v_mul_f32_e32 v51, v51, v55
	v_mul_f32_e32 v60, v60, v61
	v_mul_f32_e32 v51, v51, v54
	v_cvt_pk_bf16_f32 v59, v59, v60
	v_cvt_pk_bf16_f32 v60, v50, v51
	v_exp_f32_e64 v51, -v56
	v_mul_f32_e32 v42, v42, v46
	v_exp_f32_e64 v46, -v47
	v_mul_f32_e32 v50, v52, v56
	v_exp_f32_e64 v52, -v57
	v_add_f32_e32 v51, 1.0, v51
	v_add_f32_e32 v46, 1.0, v46
	v_rcp_f32_e32 v51, v51
	v_add_f32_e32 v52, 1.0, v52
	v_rcp_f32_e32 v46, v46
	v_rcp_f32_e32 v52, v52
	v_add_u32_e32 v66, 0x80, v150
	v_mad_i64_i32 v[66:67], s[18:19], v66, s56, v[140:141]
	v_mul_f32_e32 v43, v43, v47
	v_lshl_add_u64 v[66:67], v[66:67], 0, v[142:143]
	v_mul_f32_e32 v50, v50, v51
	v_mul_f32_e32 v51, v53, v57
	v_mul_f32_e32 v43, v43, v46
	v_mul_f32_e32 v51, v51, v52
	v_cvt_pk_bf16_f32 v61, v50, v51
	flat_store_dwordx4 v[66:67], v[58:61] sc1
	v_cvt_pk_bf16_f32 v42, v42, v43
	v_mul_f32_e32 v43, v44, v48
	v_exp_f32_e64 v44, -v48
	v_mul_f32_e32 v34, v34, v38
	v_exp_f32_e64 v38, -v38
	v_mul_f32_e32 v26, v26, v30
	v_add_f32_e32 v44, 1.0, v44
	v_rcp_f32_e32 v44, v44
	v_add_f32_e32 v38, 1.0, v38
	v_rcp_f32_e32 v38, v38
	v_exp_f32_e64 v30, -v30
	v_mul_f32_e32 v43, v43, v44
	v_mul_f32_e32 v44, v45, v49
	v_exp_f32_e64 v45, -v49
	v_mul_f32_e32 v34, v34, v38
	v_exp_f32_e64 v38, -v39
	v_add_f32_e32 v30, 1.0, v30
	v_add_f32_e32 v45, 1.0, v45
	v_rcp_f32_e32 v45, v45
	v_add_f32_e32 v38, 1.0, v38
	v_rcp_f32_e32 v38, v38
	v_rcp_f32_e32 v30, v30
	v_mul_f32_e32 v35, v35, v39
	v_mul_f32_e32 v44, v44, v45
	v_mul_f32_e32 v35, v35, v38
	v_cvt_pk_bf16_f32 v43, v43, v44
	v_cvt_pk_bf16_f32 v44, v34, v35
	v_exp_f32_e64 v35, -v40
	v_mul_f32_e32 v26, v26, v30
	v_exp_f32_e64 v30, -v31
	v_mul_f32_e32 v34, v36, v40
	v_exp_f32_e64 v36, -v41
	v_add_f32_e32 v35, 1.0, v35
	v_add_f32_e32 v30, 1.0, v30
	v_rcp_f32_e32 v35, v35
	v_add_f32_e32 v36, 1.0, v36
	v_rcp_f32_e32 v30, v30
	v_rcp_f32_e32 v36, v36
	v_add_u32_e32 v50, 0x90, v150
	v_mad_i64_i32 v[50:51], s[18:19], v50, s56, v[140:141]
	v_mul_f32_e32 v27, v27, v31
	v_lshl_add_u64 v[50:51], v[50:51], 0, v[142:143]
	v_mul_f32_e32 v34, v34, v35
	v_mul_f32_e32 v35, v37, v41
	v_mul_f32_e32 v27, v27, v30
	v_mul_f32_e32 v35, v35, v36
	v_cvt_pk_bf16_f32 v45, v34, v35
	flat_store_dwordx4 v[50:51], v[42:45] sc1
	v_cvt_pk_bf16_f32 v26, v26, v27
	v_mul_f32_e32 v27, v28, v32
	v_exp_f32_e64 v28, -v32
	v_mul_f32_e32 v18, v18, v22
	v_exp_f32_e64 v22, -v22
	v_mul_f32_e32 v10, v10, v14
	v_add_f32_e32 v28, 1.0, v28
	v_rcp_f32_e32 v28, v28
	v_add_f32_e32 v22, 1.0, v22
	v_rcp_f32_e32 v22, v22
	v_exp_f32_e64 v14, -v14
	v_mul_f32_e32 v27, v27, v28
	v_mul_f32_e32 v28, v29, v33
	v_exp_f32_e64 v29, -v33
	v_mul_f32_e32 v18, v18, v22
	v_exp_f32_e64 v22, -v23
	v_add_f32_e32 v14, 1.0, v14
	v_add_f32_e32 v29, 1.0, v29
	v_rcp_f32_e32 v29, v29
	v_add_f32_e32 v22, 1.0, v22
	v_rcp_f32_e32 v22, v22
	v_rcp_f32_e32 v14, v14
	v_mul_f32_e32 v19, v19, v23
	v_mul_f32_e32 v28, v28, v29
	v_mul_f32_e32 v19, v19, v22
	v_cvt_pk_bf16_f32 v27, v27, v28
	v_cvt_pk_bf16_f32 v28, v18, v19
	v_exp_f32_e64 v19, -v24
	v_mul_f32_e32 v10, v10, v14
	v_exp_f32_e64 v14, -v15
	v_mul_f32_e32 v18, v20, v24
	v_exp_f32_e64 v20, -v25
	v_add_f32_e32 v19, 1.0, v19
	v_add_f32_e32 v14, 1.0, v14
	v_rcp_f32_e32 v19, v19
	v_add_f32_e32 v20, 1.0, v20
	v_rcp_f32_e32 v14, v14
	v_rcp_f32_e32 v20, v20
	v_add_u32_e32 v34, 0xa0, v150
	v_mad_i64_i32 v[34:35], s[18:19], v34, s56, v[140:141]
	v_mul_f32_e32 v11, v11, v15
	v_lshl_add_u64 v[34:35], v[34:35], 0, v[142:143]
	v_mul_f32_e32 v18, v18, v19
	v_mul_f32_e32 v19, v21, v25
	v_mul_f32_e32 v11, v11, v14
	v_mul_f32_e32 v19, v19, v20
	v_cvt_pk_bf16_f32 v29, v18, v19
	flat_store_dwordx4 v[34:35], v[26:29] sc1
	v_cvt_pk_bf16_f32 v10, v10, v11
	v_mul_f32_e32 v11, v12, v16
	v_exp_f32_e64 v12, -v16
	v_mul_f32_e32 v2, v2, v6
	v_exp_f32_e64 v6, -v6
	v_mul_f32_e32 v3, v3, v7
	v_add_f32_e32 v12, 1.0, v12
	v_rcp_f32_e32 v12, v12
	v_add_f32_e32 v6, 1.0, v6
	v_rcp_f32_e32 v6, v6
	v_add_u32_e32 v18, 0xb0, v150
	v_mul_f32_e32 v11, v11, v12
	v_mul_f32_e32 v12, v13, v17
	v_exp_f32_e64 v13, -v17
	v_mul_f32_e32 v2, v2, v6
	v_exp_f32_e64 v6, -v7
	v_mad_i64_i32 v[18:19], s[18:19], v18, s56, v[140:141]
	v_add_f32_e32 v13, 1.0, v13
	v_add_f32_e32 v6, 1.0, v6
	v_rcp_f32_e32 v13, v13
	v_rcp_f32_e32 v6, v6
	v_lshl_add_u64 v[18:19], v[18:19], 0, v[142:143]
	s_mov_b64 s[18:19], -1
	v_mul_f32_e32 v12, v12, v13
	v_mul_f32_e32 v3, v3, v6
	v_cvt_pk_bf16_f32 v11, v11, v12
	v_cvt_pk_bf16_f32 v12, v2, v3
	v_exp_f32_e64 v3, -v8
	v_mul_f32_e32 v2, v4, v8
	v_exp_f32_e64 v4, -v9
	s_andn2_b64 vcc, exec, s[38:39]
	v_add_f32_e32 v3, 1.0, v3
	v_rcp_f32_e32 v3, v3
	v_add_f32_e32 v4, 1.0, v4
	v_rcp_f32_e32 v4, v4
	v_mul_f32_e32 v2, v2, v3
	v_mul_f32_e32 v3, v5, v9
	v_mul_f32_e32 v3, v3, v4
	v_cvt_pk_bf16_f32 v13, v2, v3
	flat_store_dwordx4 v[18:19], v[10:13] sc1
	s_cbranch_vccnz .LBB0_588
	s_andn2_b64 vcc, exec, s[0:1]
	s_cbranch_vccnz .LBB0_587
	s_barrier
	s_branch .LBB0_587
